# P5 unit order changed to 2 panels x 16 column tiles per XCD round (full output rows per XCD at a time), on top of MFMA chain+snake order
# speedup vs baseline: 1.0233x; 1.0024x over previous
.Lsp_p5:
	s_lshl_b32 s35, s3, 10
	v_add_lshl_u32 v164, v5, v16, 1
	v_and_b32_e32 v4, 0x7fff0, v4
	v_lshlrev_b32_e32 v5, 5, v18
	v_sub_u32_e32 v1, v1, v2
	s_lshr_b32 s14, s82, 4
	s_lshl_b32 s14, s14, 21
	v_add_u32_e32 v4, v17, v4
	v_and_b32_e32 v19, 32, v5
	v_ashrrev_i16_sdwa v1, v6, sext(v1) dst_sel:DWORD dst_unused:UNUSED_PAD src0_sel:DWORD src1_sel:BYTE_0
	s_mov_b32 s15, 0
	s_add_u32 s14, s30, s14
	v_lshl_or_b32 v4, v4, 12, v19
	v_bfe_i32 v20, v1, 0, 16
	s_addc_u32 s15, s31, s15
	s_add_i32 s36, s35, 0
	v_add_lshl_u32 v2, v4, v20, 1
	s_add_i32 m0, s36, 0x10000
	v_mov_b32_e32 v165, v3
	global_load_lds_dwordx4 v2, s[14:15]
	s_add_i32 m0, s36, 0x12000
	s_add_u32 s16, s14, 0x100000
	global_load_lds_dwordx4 v164, s[14:15]
	s_addc_u32 s17, s15, 0
	s_add_i32 m0, s36, 0x14000
	v_lshl_add_u64 v[10:11], s[14:15], 0, v[2:3]
	global_load_lds_dwordx4 v2, s[16:17]
	s_add_i32 m0, s36, 0x16000
	v_lshl_add_u64 v[8:9], s[14:15], 0, v[164:165]
	global_load_lds_dwordx4 v164, s[16:17]
	s_and_b32 s16, s82, 7
	s_lshl_b32 s16, s16, 3
	s_bfe_u32 s17, s82, 0x10003
	s_add_i32 s16, s16, s17
	s_lshl_b32 s16, s16, 21
	s_mov_b32 s17, 0
	s_add_u32 s60, s26, s16
	s_addc_u32 s61, s27, s17
	s_add_i32 s37, s36, 0x2000
	s_mov_b32 m0, s36
	s_add_u32 s16, s60, 0x100000
	global_load_lds_dwordx4 v2, s[60:61]
	s_mov_b32 m0, s37
	s_addc_u32 s17, s61, 0
	s_add_i32 s62, s36, 0x4000
	global_load_lds_dwordx4 v164, s[60:61]
	s_mov_b32 m0, s62
	s_add_i32 s63, s36, 0x6000
	global_load_lds_dwordx4 v2, s[16:17]
	s_mov_b32 m0, s63
	s_cmp_eq_u32 s1, 1
	global_load_lds_dwordx4 v164, s[16:17]
	s_load_dwordx2 s[16:17], s[12:13], 0x0
	v_lshl_add_u64 v[4:5], s[60:61], 0, v[2:3]
	s_cselect_b64 s[22:23], -1, 0
	s_cmp_lg_u32 s1, 1
	v_lshl_add_u64 v[6:7], s[60:61], 0, v[164:165]
	s_cbranch_scc1 .LBB0_1003
	s_barrier
.LBB0_1003:
	s_lshl_b32 s76, s44, 12
	s_add_u32 s12, s50, 0x18000000
	s_addc_u32 s13, s51, 0
	s_lshl_b64 s[24:25], s[76:77], 2
	s_add_u32 s44, s18, s24
	s_addc_u32 s45, s19, s25
	s_add_u32 s46, s50, 0x5b000000
	s_addc_u32 s47, s51, 0
	s_and_b32 s64, s3, 3
	s_add_i32 m0, s36, 0x18000
	v_lshl_add_u64 v[10:11], v[10:11], 0, s[4:5]
	s_lshl_b32 s3, s1, 13
	s_lshl_b32 s24, s64, 12
	s_waitcnt vmcnt(2)
	s_barrier
	global_load_lds_dwordx4 v[10:11], off
	v_lshl_add_u64 v[8:9], v[8:9], 0, s[4:5]
	s_add_i32 m0, s36, 0x1a000
	s_add_i32 s65, s36, 0x8000
	s_add_i32 s66, s36, 0xa000
	global_load_lds_dwordx4 v[8:9], off
	v_lshl_add_u64 v[4:5], v[4:5], 0, s[4:5]
	s_mov_b32 m0, s65
	s_add_u32 s18, s14, 0x100080
	global_load_lds_dwordx4 v[4:5], off
	v_lshl_add_u64 v[4:5], v[6:7], 0, s[4:5]
	s_mov_b32 m0, s66
	s_addc_u32 s19, s15, 0
	global_load_lds_dwordx4 v[4:5], off
	s_add_i32 m0, s36, 0x1c000
	v_lshl_add_u64 v[4:5], s[18:19], 0, v[2:3]
	global_load_lds_dwordx4 v[4:5], off
	v_lshl_add_u64 v[4:5], s[18:19], 0, v[164:165]
	s_add_i32 m0, s36, 0x1e000
	s_cmpk_lt_u32 s0, 0x100
	global_load_lds_dwordx4 v[4:5], off
	v_bfe_u32 v4, v12, 4, 2
	v_and_b32_e32 v5, 15, v12
	v_lshlrev_b32_e32 v6, 4, v4
	v_lshl_or_b32 v1, s1, 6, v5
	v_lshl_or_b32 v5, v5, 6, v6
	v_lshlrev_b32_e32 v6, 2, v12
	v_and_b32_e32 v6, 32, v6
	v_bitop3_b32 v7, v5, s3, v6 bitop3:0xde
	v_bitop3_b32 v178, v5, s24, v6 bitop3:0xde
	v_lshlrev_b32_e32 v5, 2, v4
	v_cmp_eq_u32_e64 s[40:41], 0, v4
	v_lshlrev_b32_e32 v4, 15, v18
	v_and_b32_e32 v4, 0x7fff0000, v4
	v_lshl_add_u32 v4, v17, 12, v4
	v_or_b32_e32 v4, v4, v19
	v_lshl_or_b32 v179, s64, 5, v5
	v_add_lshl_u32 v4, v4, v20, 1
	v_mov_b32_e32 v5, v3
	s_mov_b64 s[0:1], 0x100080
	v_lshl_add_u64 v[166:167], v[4:5], 0, s[0:1]
	v_lshlrev_b32_e32 v4, 15, v13
	v_and_b32_e32 v4, 0x7fff0000, v4
	v_lshl_add_u32 v4, v14, 12, v4
	s_waitcnt vmcnt(6)
	v_or_b32_e32 v4, v4, v15
	v_add_lshl_u32 v4, v4, v16, 1
	s_cselect_b64 s[50:51], -1, 0
	s_and_b32 s18, s82, 7
	s_lshl_b32 s18, s18, 3
	s_bfe_u32 s19, s82, 0x10003
	s_add_i32 s18, s18, s19
	s_mov_b32 s67, 0
	v_lshl_add_u64 v[168:169], v[4:5], 0, s[0:1]
	v_add_u32_e32 v180, 0, v7
	s_lshr_b32 s0, s82, 4
	s_mov_b32 s1, s18
	s_barrier
	s_mov_b32 s19, 0
	s_branch .LBB0_1006

.LBB0_1012:
	s_and_b32 s18, s82, 7
	s_lshl_b32 s18, s18, 3
	s_bfe_u32 s19, s82, 0x10003
	s_add_i32 s18, s18, s19
	s_lshl_b32 s19, s67, 1
	s_add_i32 s54, s18, s19
	s_lshr_b32 s52, s82, 4
	s_ashr_i32 s55, s54, 31
	s_lshl_b64 s[18:19], s[54:55], 21
	s_add_u32 s56, s26, s18
	s_addc_u32 s57, s27, s19
	s_and_b64 s[18:19], s[42:43], exec
	s_cselect_b32 s3, s57, s61
	s_cselect_b32 s28, s56, s60
	s_ashr_i32 s53, s52, 31
	s_lshl_b64 s[18:19], s[52:53], 21
	s_add_u32 s58, s30, s18
	s_addc_u32 s59, s31, s19
	s_and_b64 s[18:19], s[42:43], exec
	s_cselect_b32 s29, s59, s15
	s_cselect_b32 s53, s58, s14
	s_add_u32 s55, s14, 0x100
	v_mov_b32_e32 v4, 0
	s_addc_u32 s68, s15, 0
	s_mov_b32 s69, -2
	s_waitcnt lgkmcnt(0)
	v_mov_b32_e32 v5, v4
	v_mov_b64_e32 v[6:7], v[4:5]
	v_mov_b64_e32 v[8:9], v[4:5]
	v_mov_b64_e32 v[10:11], v[4:5]
	v_mov_b64_e32 v[12:13], v[4:5]
	v_mov_b64_e32 v[14:15], v[4:5]
	v_mov_b64_e32 v[16:17], v[4:5]
	v_mov_b64_e32 v[18:19], v[4:5]
	v_mov_b64_e32 v[20:21], v[4:5]
	v_mov_b64_e32 v[22:23], v[4:5]
	v_mov_b64_e32 v[24:25], v[4:5]
	v_mov_b64_e32 v[26:27], v[4:5]
	v_mov_b64_e32 v[28:29], v[4:5]
	v_mov_b64_e32 v[30:31], v[4:5]
	v_mov_b64_e32 v[32:33], v[4:5]
	v_mov_b64_e32 v[34:35], v[4:5]
	v_mov_b64_e32 v[36:37], v[4:5]
	v_mov_b64_e32 v[38:39], v[4:5]
	v_mov_b64_e32 v[40:41], v[4:5]
	v_mov_b64_e32 v[42:43], v[4:5]
	v_mov_b64_e32 v[44:45], v[4:5]
	v_mov_b64_e32 v[46:47], v[4:5]
	v_mov_b64_e32 v[52:53], v[4:5]
	v_mov_b64_e32 v[54:55], v[4:5]
	v_mov_b64_e32 v[68:69], v[4:5]
	v_mov_b64_e32 v[70:71], v[4:5]
	v_mov_b64_e32 v[72:73], v[4:5]
	v_mov_b64_e32 v[74:75], v[4:5]
	v_mov_b64_e32 v[76:77], v[4:5]
	v_mov_b64_e32 v[78:79], v[4:5]
	v_mov_b64_e32 v[80:81], v[4:5]
	v_mov_b64_e32 v[82:83], v[4:5]
	v_mov_b64_e32 v[84:85], v[4:5]
	v_mov_b64_e32 v[86:87], v[4:5]
	v_mov_b64_e32 v[88:89], v[4:5]
	v_mov_b64_e32 v[90:91], v[4:5]
	v_mov_b64_e32 v[92:93], v[4:5]
	v_mov_b64_e32 v[94:95], v[4:5]
	v_mov_b64_e32 v[96:97], v[4:5]
	v_mov_b64_e32 v[98:99], v[4:5]
	v_mov_b64_e32 v[100:101], v[4:5]
	v_mov_b64_e32 v[102:103], v[4:5]
	v_mov_b64_e32 v[104:105], v[4:5]
	v_mov_b64_e32 v[106:107], v[4:5]
	v_mov_b64_e32 v[108:109], v[4:5]
	v_mov_b64_e32 v[110:111], v[4:5]
	v_mov_b64_e32 v[112:113], v[4:5]
	v_mov_b64_e32 v[114:115], v[4:5]
	v_mov_b64_e32 v[116:117], v[4:5]
	v_mov_b64_e32 v[118:119], v[4:5]
	v_mov_b64_e32 v[120:121], v[4:5]
	v_mov_b64_e32 v[122:123], v[4:5]
	v_mov_b64_e32 v[124:125], v[4:5]
	v_mov_b64_e32 v[126:127], v[4:5]
	v_mov_b64_e32 v[128:129], v[4:5]
	v_mov_b64_e32 v[130:131], v[4:5]
	v_mov_b64_e32 v[132:133], v[4:5]
	v_mov_b64_e32 v[134:135], v[4:5]
	v_mov_b64_e32 v[136:137], v[4:5]
	v_mov_b64_e32 v[138:139], v[4:5]
	v_mov_b64_e32 v[140:141], v[4:5]
	v_mov_b64_e32 v[142:143], v[4:5]
	v_mov_b64_e32 v[144:145], v[4:5]
	v_mov_b64_e32 v[146:147], v[4:5]
